# adds: first K-loop iteration of six GEMM sites peeled with C=0 on each accumulator's first MFMA, accumulator zero-fill removed
# speedup vs baseline: 1.0066x; 1.0031x over previous
.Lzgo_1:
	s_add_u32 s22, s22, 0x80
	s_addc_u32 s23, s23, 0
	s_add_u32 vcc_lo, s66, 0x100
	s_addc_u32 vcc_hi, s67, 0
	s_mov_b32 s66, 0
	s_add_i32 s88, s66, 2
	s_add_u32 s62, s22, 0x80
	s_addc_u32 s63, s23, 0
	s_add_i32 s89, 0, 0x10000
	s_cmp_eq_u32 s93, s66
	s_cselect_b32 s67, s3, s63
	s_cselect_b32 s66, s2, s62
	v_add_u32_e32 v149, s89, v146
	s_cselect_b32 s63, s21, vcc_hi
	s_cselect_b32 s62, s20, vcc_lo
	s_add_i32 s31, 0, 0x14000
	ds_read_b128 v[142:145], v149
	ds_read_b128 v[150:153], v149 offset:1024
	ds_read_b128 v[154:157], v149 offset:2048
	ds_read_b128 v[158:161], v149 offset:3072
	v_add_u32_e32 v149, s31, v146
	ds_read_b128 v[162:165], v149
	ds_read_b128 v[166:169], v149 offset:1024
	ds_read_b128 v[170:173], v149 offset:2048
	ds_read_b128 v[174:177], v149 offset:3072
	v_lshl_add_u64 v[218:219], s[22:23], 0, v[138:139]
	s_add_i32 m0, s77, 0xc000
	ds_read_b128 v[178:181], v148
	ds_read_b128 v[182:185], v148 offset:1024
	ds_read_b128 v[186:189], v148 offset:2048
	ds_read_b128 v[190:193], v148 offset:3072
	ds_read_b128 v[194:197], v148 offset:4096
	ds_read_b128 v[198:201], v148 offset:5120
	ds_read_b128 v[202:205], v148 offset:6144
	ds_read_b128 v[214:217], v148 offset:7168
	global_load_lds_dwordx4 v[218:219], off
	v_lshl_add_u64 v[218:219], s[22:23], 0, v[140:141]
	s_add_i32 m0, s77, 0xe000
	s_nop 0
	global_load_lds_dwordx4 v[218:219], off
	s_waitcnt vmcnt(8)
	s_waitcnt lgkmcnt(0)
	s_barrier
	s_setprio 1
	s_waitcnt lgkmcnt(0)
	v_mfma_f32_16x16x32_bf16 v[122:125], v[142:145], v[178:181], 0
	v_mfma_f32_16x16x32_bf16 v[118:121], v[154:157], v[178:181], 0
	v_mfma_f32_16x16x32_bf16 v[110:113], v[142:145], v[186:189], 0
	v_mfma_f32_16x16x32_bf16 v[102:105], v[154:157], v[186:189], 0
	v_mfma_f32_16x16x32_bf16 v[94:97], v[142:145], v[194:197], 0
	v_mfma_f32_16x16x32_bf16 v[86:89], v[154:157], v[194:197], 0
	v_mfma_f32_16x16x32_bf16 v[78:81], v[142:145], v[202:205], 0
	v_mfma_f32_16x16x32_bf16 v[70:73], v[154:157], v[202:205], 0
	v_mfma_f32_16x16x32_bf16 v[122:125], v[150:153], v[182:185], v[122:125]
	v_mfma_f32_16x16x32_bf16 v[118:121], v[158:161], v[182:185], v[118:121]
	v_mfma_f32_16x16x32_bf16 v[110:113], v[150:153], v[190:193], v[110:113]
	v_mfma_f32_16x16x32_bf16 v[102:105], v[158:161], v[190:193], v[102:105]
	v_mfma_f32_16x16x32_bf16 v[94:97], v[150:153], v[198:201], v[94:97]
	v_mfma_f32_16x16x32_bf16 v[86:89], v[158:161], v[198:201], v[86:89]
	v_mfma_f32_16x16x32_bf16 v[78:81], v[150:153], v[214:217], v[78:81]
	v_mfma_f32_16x16x32_bf16 v[70:73], v[158:161], v[214:217], v[70:73]
	s_setprio 0
	s_setprio 1
	v_mfma_f32_16x16x32_bf16 v[126:129], v[162:165], v[178:181], 0
	v_mfma_f32_16x16x32_bf16 v[114:117], v[170:173], v[178:181], 0
	v_mfma_f32_16x16x32_bf16 v[106:109], v[162:165], v[186:189], 0
	v_mfma_f32_16x16x32_bf16 v[98:101], v[170:173], v[186:189], 0
	v_mfma_f32_16x16x32_bf16 v[90:93], v[162:165], v[194:197], 0
	v_mfma_f32_16x16x32_bf16 v[82:85], v[170:173], v[194:197], 0
	v_mfma_f32_16x16x32_bf16 v[74:77], v[162:165], v[202:205], 0
	v_mfma_f32_16x16x32_bf16 v[66:69], v[170:173], v[202:205], 0
	v_mfma_f32_16x16x32_bf16 v[126:129], v[166:169], v[182:185], v[126:129]
	v_mfma_f32_16x16x32_bf16 v[114:117], v[174:177], v[182:185], v[114:117]
	v_mfma_f32_16x16x32_bf16 v[106:109], v[166:169], v[190:193], v[106:109]
	v_mfma_f32_16x16x32_bf16 v[98:101], v[174:177], v[190:193], v[98:101]
	v_mfma_f32_16x16x32_bf16 v[90:93], v[166:169], v[198:201], v[90:93]
	v_mfma_f32_16x16x32_bf16 v[82:85], v[174:177], v[198:201], v[82:85]
	v_mfma_f32_16x16x32_bf16 v[74:77], v[166:169], v[214:217], v[74:77]
	v_mfma_f32_16x16x32_bf16 v[66:69], v[174:177], v[214:217], v[66:69]
	s_setprio 0
	s_barrier
	s_add_i32 s89, s89, s74
	v_lshl_add_u64 v[218:219], s[62:63], 0, v[134:135]
	s_mov_b32 m0, s89
	ds_read_b128 v[178:181], v148 offset:16384
	ds_read_b128 v[182:185], v148 offset:17408
	ds_read_b128 v[186:189], v148 offset:18432
	ds_read_b128 v[190:193], v148 offset:19456
	ds_read_b128 v[194:197], v148 offset:20480
	ds_read_b128 v[198:201], v148 offset:21504
	ds_read_b128 v[202:205], v148 offset:22528
	ds_read_b128 v[214:217], v148 offset:23552
	global_load_lds_dwordx4 v[218:219], off
	s_add_i32 m0, s89, 0x2000
	v_lshl_add_u64 v[220:221], s[62:63], 0, v[130:131]
	s_add_u32 s62, s62, s8
	s_addc_u32 s63, s63, s9
	s_add_i32 s31, s31, s74
	global_load_lds_dwordx4 v[220:221], off
	v_lshl_add_u64 v[222:223], s[62:63], 0, v[134:135]
	s_mov_b32 m0, s31
	v_lshl_add_u64 v[224:225], s[62:63], 0, v[130:131]
	global_load_lds_dwordx4 v[222:223], off
	s_add_i32 m0, s31, 0x2000
	v_lshl_add_u64 v[226:227], s[66:67], 0, v[136:137]
	global_load_lds_dwordx4 v[224:225], off
	s_mov_b32 m0, s77
	v_lshl_add_u64 v[236:237], s[66:67], 0, v[132:133]
	global_load_lds_dwordx4 v[226:227], off
	s_mov_b32 m0, s78
	s_nop 0
	global_load_lds_dwordx4 v[236:237], off
	s_waitcnt vmcnt(8)
	s_waitcnt lgkmcnt(0)
	s_barrier
	s_setprio 1
	s_waitcnt lgkmcnt(0)
	v_mfma_f32_16x16x32_bf16 v[62:65], v[142:145], v[178:181], 0
	v_mfma_f32_16x16x32_bf16 v[54:57], v[154:157], v[178:181], 0
	v_mfma_f32_16x16x32_bf16 v[46:49], v[142:145], v[186:189], 0
	v_mfma_f32_16x16x32_bf16 v[38:41], v[154:157], v[186:189], 0
	v_mfma_f32_16x16x32_bf16 v[30:33], v[142:145], v[194:197], 0
	v_mfma_f32_16x16x32_bf16 v[22:25], v[154:157], v[194:197], 0
	v_mfma_f32_16x16x32_bf16 v[14:17], v[142:145], v[202:205], 0
	v_mfma_f32_16x16x32_bf16 v[6:9], v[154:157], v[202:205], 0
	v_mfma_f32_16x16x32_bf16 v[62:65], v[150:153], v[182:185], v[62:65]
	v_mfma_f32_16x16x32_bf16 v[54:57], v[158:161], v[182:185], v[54:57]
	v_mfma_f32_16x16x32_bf16 v[46:49], v[150:153], v[190:193], v[46:49]
	v_mfma_f32_16x16x32_bf16 v[38:41], v[158:161], v[190:193], v[38:41]
	v_mfma_f32_16x16x32_bf16 v[30:33], v[150:153], v[198:201], v[30:33]
	v_mfma_f32_16x16x32_bf16 v[22:25], v[158:161], v[198:201], v[22:25]
	v_mfma_f32_16x16x32_bf16 v[14:17], v[150:153], v[214:217], v[14:17]
	v_mfma_f32_16x16x32_bf16 v[6:9], v[158:161], v[214:217], v[6:9]
	s_setprio 0
	s_setprio 1
	v_mfma_f32_16x16x32_bf16 v[58:61], v[162:165], v[178:181], 0
	v_mfma_f32_16x16x32_bf16 v[50:53], v[170:173], v[178:181], 0
	v_mfma_f32_16x16x32_bf16 v[42:45], v[162:165], v[186:189], 0
	v_mfma_f32_16x16x32_bf16 v[34:37], v[170:173], v[186:189], 0
	v_mfma_f32_16x16x32_bf16 v[26:29], v[162:165], v[194:197], 0
	v_mfma_f32_16x16x32_bf16 v[18:21], v[170:173], v[194:197], 0
	v_mfma_f32_16x16x32_bf16 v[10:13], v[162:165], v[202:205], 0
	v_mfma_f32_16x16x32_bf16 v[2:5], v[170:173], v[202:205], 0
	v_mfma_f32_16x16x32_bf16 v[58:61], v[166:169], v[182:185], v[58:61]
	v_mfma_f32_16x16x32_bf16 v[50:53], v[174:177], v[182:185], v[50:53]
	v_mfma_f32_16x16x32_bf16 v[42:45], v[166:169], v[190:193], v[42:45]
	v_mfma_f32_16x16x32_bf16 v[34:37], v[174:177], v[190:193], v[34:37]
	v_mfma_f32_16x16x32_bf16 v[26:29], v[166:169], v[198:201], v[26:29]
	v_mfma_f32_16x16x32_bf16 v[18:21], v[174:177], v[198:201], v[18:21]
	v_mfma_f32_16x16x32_bf16 v[10:13], v[166:169], v[214:217], v[10:13]
	v_mfma_f32_16x16x32_bf16 v[2:5], v[174:177], v[214:217], v[2:5]
	s_setprio 0
	s_barrier
	s_add_i32 s31, 0, 0x18000
	v_add_u32_e32 v149, s31, v146
	s_add_i32 s89, 0, 0x1c000
	ds_read_b128 v[142:145], v149
	ds_read_b128 v[150:153], v149 offset:1024
	ds_read_b128 v[154:157], v149 offset:2048
	ds_read_b128 v[158:161], v149 offset:3072
	v_add_u32_e32 v149, s89, v146
	ds_read_b128 v[162:165], v149
	ds_read_b128 v[166:169], v149 offset:1024
	ds_read_b128 v[170:173], v149 offset:2048
	ds_read_b128 v[174:177], v149 offset:3072
	s_add_u32 s62, s66, s8
	s_addc_u32 s63, s67, s9
	s_mov_b32 m0, s79
	v_lshl_add_u64 v[238:239], s[62:63], 0, v[136:137]
	ds_read_b128 v[178:181], v148 offset:32768
	ds_read_b128 v[182:185], v148 offset:33792
	ds_read_b128 v[186:189], v148 offset:34816
	ds_read_b128 v[190:193], v148 offset:35840
	ds_read_b128 v[194:197], v148 offset:36864
	ds_read_b128 v[198:201], v148 offset:37888
	ds_read_b128 v[202:205], v148 offset:38912
	ds_read_b128 v[214:217], v148 offset:39936
	global_load_lds_dwordx4 v[238:239], off
	v_lshl_add_u64 v[238:239], s[62:63], 0, v[132:133]
	s_mov_b32 m0, s90
	s_nop 0
	global_load_lds_dwordx4 v[238:239], off
	s_waitcnt vmcnt(8)
	s_waitcnt lgkmcnt(0)
	s_barrier
	s_setprio 1
	s_waitcnt lgkmcnt(0)
	v_mfma_f32_16x16x32_bf16 v[122:125], v[142:145], v[178:181], v[122:125]
	v_mfma_f32_16x16x32_bf16 v[118:121], v[154:157], v[178:181], v[118:121]
	v_mfma_f32_16x16x32_bf16 v[110:113], v[142:145], v[186:189], v[110:113]
	v_mfma_f32_16x16x32_bf16 v[102:105], v[154:157], v[186:189], v[102:105]
	v_mfma_f32_16x16x32_bf16 v[94:97], v[142:145], v[194:197], v[94:97]
	v_mfma_f32_16x16x32_bf16 v[86:89], v[154:157], v[194:197], v[86:89]
	v_mfma_f32_16x16x32_bf16 v[78:81], v[142:145], v[202:205], v[78:81]
	v_mfma_f32_16x16x32_bf16 v[70:73], v[154:157], v[202:205], v[70:73]
	v_mfma_f32_16x16x32_bf16 v[122:125], v[150:153], v[182:185], v[122:125]
	v_mfma_f32_16x16x32_bf16 v[118:121], v[158:161], v[182:185], v[118:121]
	v_mfma_f32_16x16x32_bf16 v[110:113], v[150:153], v[190:193], v[110:113]
	v_mfma_f32_16x16x32_bf16 v[102:105], v[158:161], v[190:193], v[102:105]
	v_mfma_f32_16x16x32_bf16 v[94:97], v[150:153], v[198:201], v[94:97]
	v_mfma_f32_16x16x32_bf16 v[86:89], v[158:161], v[198:201], v[86:89]
	v_mfma_f32_16x16x32_bf16 v[78:81], v[150:153], v[214:217], v[78:81]
	v_mfma_f32_16x16x32_bf16 v[70:73], v[158:161], v[214:217], v[70:73]
	s_setprio 0
	s_setprio 1
	v_mfma_f32_16x16x32_bf16 v[126:129], v[162:165], v[178:181], v[126:129]
	v_mfma_f32_16x16x32_bf16 v[114:117], v[170:173], v[178:181], v[114:117]
	v_mfma_f32_16x16x32_bf16 v[106:109], v[162:165], v[186:189], v[106:109]
	v_mfma_f32_16x16x32_bf16 v[98:101], v[170:173], v[186:189], v[98:101]
	v_mfma_f32_16x16x32_bf16 v[90:93], v[162:165], v[194:197], v[90:93]
	v_mfma_f32_16x16x32_bf16 v[82:85], v[170:173], v[194:197], v[82:85]
	v_mfma_f32_16x16x32_bf16 v[74:77], v[162:165], v[202:205], v[74:77]
	v_mfma_f32_16x16x32_bf16 v[66:69], v[170:173], v[202:205], v[66:69]
	v_mfma_f32_16x16x32_bf16 v[126:129], v[166:169], v[182:185], v[126:129]
	v_mfma_f32_16x16x32_bf16 v[114:117], v[174:177], v[182:185], v[114:117]
	v_mfma_f32_16x16x32_bf16 v[106:109], v[166:169], v[190:193], v[106:109]
	v_mfma_f32_16x16x32_bf16 v[98:101], v[174:177], v[190:193], v[98:101]
	v_mfma_f32_16x16x32_bf16 v[90:93], v[166:169], v[198:201], v[90:93]
	v_mfma_f32_16x16x32_bf16 v[82:85], v[174:177], v[198:201], v[82:85]
	v_mfma_f32_16x16x32_bf16 v[74:77], v[166:169], v[214:217], v[74:77]
	v_mfma_f32_16x16x32_bf16 v[66:69], v[174:177], v[214:217], v[66:69]
	s_setprio 0
	s_barrier
	s_add_i32 s31, s31, s74
	v_lshl_add_u64 v[218:219], v[218:219], 0, s[60:61]
	s_mov_b32 m0, s31
	ds_read_b128 v[178:181], v148 offset:49152
	ds_read_b128 v[182:185], v148 offset:50176
	ds_read_b128 v[186:189], v148 offset:51200
	ds_read_b128 v[190:193], v148 offset:52224
	ds_read_b128 v[194:197], v148 offset:53248
	ds_read_b128 v[198:201], v148 offset:54272
	ds_read_b128 v[202:205], v148 offset:55296
	ds_read_b128 v[214:217], v148 offset:56320
	global_load_lds_dwordx4 v[218:219], off
	v_lshl_add_u64 v[218:219], v[220:221], 0, s[60:61]
	s_add_i32 m0, s31, 0x2000
	s_add_i32 s31, s89, s74
	global_load_lds_dwordx4 v[218:219], off
	v_lshl_add_u64 v[218:219], v[222:223], 0, s[60:61]
	s_mov_b32 m0, s31
	s_nop 0
	global_load_lds_dwordx4 v[218:219], off
	v_lshl_add_u64 v[218:219], v[224:225], 0, s[60:61]
	s_add_i32 m0, s31, 0x2000
	s_nop 0
	global_load_lds_dwordx4 v[218:219], off
	v_lshl_add_u64 v[218:219], v[226:227], 0, s[60:61]
	s_mov_b32 m0, s91
	s_nop 0
	global_load_lds_dwordx4 v[218:219], off
	v_lshl_add_u64 v[218:219], v[236:237], 0, s[60:61]
	s_mov_b32 m0, s92
	s_nop 0
	global_load_lds_dwordx4 v[218:219], off
	s_waitcnt vmcnt(8)
	s_waitcnt lgkmcnt(0)
	s_barrier
	s_setprio 1
	s_waitcnt lgkmcnt(0)
	v_mfma_f32_16x16x32_bf16 v[62:65], v[142:145], v[178:181], v[62:65]
	v_mfma_f32_16x16x32_bf16 v[54:57], v[154:157], v[178:181], v[54:57]
	v_mfma_f32_16x16x32_bf16 v[46:49], v[142:145], v[186:189], v[46:49]
	v_mfma_f32_16x16x32_bf16 v[38:41], v[154:157], v[186:189], v[38:41]
	v_mfma_f32_16x16x32_bf16 v[30:33], v[142:145], v[194:197], v[30:33]
	v_mfma_f32_16x16x32_bf16 v[22:25], v[154:157], v[194:197], v[22:25]
	v_mfma_f32_16x16x32_bf16 v[14:17], v[142:145], v[202:205], v[14:17]
	v_mfma_f32_16x16x32_bf16 v[6:9], v[154:157], v[202:205], v[6:9]
	v_mfma_f32_16x16x32_bf16 v[62:65], v[150:153], v[182:185], v[62:65]
	v_mfma_f32_16x16x32_bf16 v[54:57], v[158:161], v[182:185], v[54:57]
	v_mfma_f32_16x16x32_bf16 v[46:49], v[150:153], v[190:193], v[46:49]
	v_mfma_f32_16x16x32_bf16 v[38:41], v[158:161], v[190:193], v[38:41]
	v_mfma_f32_16x16x32_bf16 v[30:33], v[150:153], v[198:201], v[30:33]
	v_mfma_f32_16x16x32_bf16 v[22:25], v[158:161], v[198:201], v[22:25]
	v_mfma_f32_16x16x32_bf16 v[14:17], v[150:153], v[214:217], v[14:17]
	v_mfma_f32_16x16x32_bf16 v[6:9], v[158:161], v[214:217], v[6:9]
	s_setprio 0
	s_setprio 1
	v_mfma_f32_16x16x32_bf16 v[58:61], v[162:165], v[178:181], v[58:61]
	v_mfma_f32_16x16x32_bf16 v[50:53], v[170:173], v[178:181], v[50:53]
	v_mfma_f32_16x16x32_bf16 v[42:45], v[162:165], v[186:189], v[42:45]
	v_mfma_f32_16x16x32_bf16 v[34:37], v[170:173], v[186:189], v[34:37]
	v_mfma_f32_16x16x32_bf16 v[26:29], v[162:165], v[194:197], v[26:29]
	v_mfma_f32_16x16x32_bf16 v[18:21], v[170:173], v[194:197], v[18:21]
	v_mfma_f32_16x16x32_bf16 v[10:13], v[162:165], v[202:205], v[10:13]
	v_mfma_f32_16x16x32_bf16 v[2:5], v[170:173], v[202:205], v[2:5]
	v_mfma_f32_16x16x32_bf16 v[58:61], v[166:169], v[182:185], v[58:61]
	v_mfma_f32_16x16x32_bf16 v[50:53], v[174:177], v[182:185], v[50:53]
	v_mfma_f32_16x16x32_bf16 v[42:45], v[166:169], v[190:193], v[42:45]
	v_mfma_f32_16x16x32_bf16 v[34:37], v[174:177], v[190:193], v[34:37]
	v_mfma_f32_16x16x32_bf16 v[26:29], v[166:169], v[198:201], v[26:29]
	v_mfma_f32_16x16x32_bf16 v[18:21], v[174:177], v[198:201], v[18:21]
	v_mfma_f32_16x16x32_bf16 v[10:13], v[166:169], v[214:217], v[10:13]
	v_mfma_f32_16x16x32_bf16 v[2:5], v[174:177], v[214:217], v[2:5]
	s_setprio 0
	s_barrier
	s_add_u32 s22, s22, 0x100
	s_addc_u32 s23, s23, 0
	s_add_u32 vcc_lo, vcc_lo, 0x100
	s_addc_u32 vcc_hi, vcc_hi, 0
	s_cmp_ge_i32 s88, s52
	s_mov_b32 s66, s88
	s_cbranch_scc1 .LBB0_288

.Lzgo_2:
	s_add_u32 s20, s20, 0x80
	s_addc_u32 s21, s21, 0
	s_add_u32 vcc_lo, s22, 0x100
	s_addc_u32 vcc_hi, s23, 0
	s_mov_b32 s22, 0
	s_add_i32 s88, s22, 2
	s_add_u32 s31, s20, 0x80
	s_addc_u32 s23, s21, 0
	s_add_i32 s89, 0, 0x10000
	s_cmp_eq_u32 s90, s22
	s_cselect_b32 s23, s3, s23
	s_cselect_b32 s22, s2, s31
	v_add_u32_e32 v146, s89, v148
	s_cselect_b32 s63, s19, vcc_hi
	s_cselect_b32 s62, s18, vcc_lo
	s_add_i32 s31, 0, 0x14000
	ds_read_b128 v[138:141], v146
	ds_read_b128 v[142:145], v146 offset:1024
	ds_read_b128 v[152:155], v146 offset:2048
	ds_read_b128 v[156:159], v146 offset:3072
	v_add_u32_e32 v146, s31, v148
	ds_read_b128 v[160:163], v146
	ds_read_b128 v[164:167], v146 offset:1024
	ds_read_b128 v[168:171], v146 offset:2048
	ds_read_b128 v[172:175], v146 offset:3072
	v_lshl_add_u64 v[146:147], s[20:21], 0, v[134:135]
	s_add_i32 m0, s67, 0xc000
	ds_read_b128 v[176:179], v150
	ds_read_b128 v[180:183], v150 offset:1024
	ds_read_b128 v[184:187], v150 offset:2048
	ds_read_b128 v[188:191], v150 offset:3072
	ds_read_b128 v[192:195], v150 offset:4096
	ds_read_b128 v[196:199], v150 offset:5120
	ds_read_b128 v[200:203], v150 offset:6144
	ds_read_b128 v[214:217], v150 offset:7168
	global_load_lds_dwordx4 v[146:147], off
	v_lshl_add_u64 v[146:147], s[20:21], 0, v[136:137]
	s_add_i32 m0, s67, 0xe000
	s_nop 0
	global_load_lds_dwordx4 v[146:147], off
	s_waitcnt vmcnt(8)
	s_waitcnt lgkmcnt(0)
	s_barrier
	s_setprio 1
	s_waitcnt lgkmcnt(0)
	v_mfma_f32_16x16x32_bf16 v[126:129], v[138:141], v[176:179], 0
	v_mfma_f32_16x16x32_bf16 v[94:97], v[152:155], v[176:179], 0
	v_mfma_f32_16x16x32_bf16 v[122:125], v[138:141], v[184:187], 0
	v_mfma_f32_16x16x32_bf16 v[90:93], v[152:155], v[184:187], 0
	v_mfma_f32_16x16x32_bf16 v[118:121], v[138:141], v[192:195], 0
	v_mfma_f32_16x16x32_bf16 v[86:89], v[152:155], v[192:195], 0
	v_mfma_f32_16x16x32_bf16 v[114:117], v[138:141], v[200:203], 0
	v_mfma_f32_16x16x32_bf16 v[82:85], v[152:155], v[200:203], 0
	v_mfma_f32_16x16x32_bf16 v[126:129], v[142:145], v[180:183], v[126:129]
	v_mfma_f32_16x16x32_bf16 v[94:97], v[156:159], v[180:183], v[94:97]
	v_mfma_f32_16x16x32_bf16 v[122:125], v[142:145], v[188:191], v[122:125]
	v_mfma_f32_16x16x32_bf16 v[90:93], v[156:159], v[188:191], v[90:93]
	v_mfma_f32_16x16x32_bf16 v[118:121], v[142:145], v[196:199], v[118:121]
	v_mfma_f32_16x16x32_bf16 v[86:89], v[156:159], v[196:199], v[86:89]
	v_mfma_f32_16x16x32_bf16 v[114:117], v[142:145], v[214:217], v[114:117]
	v_mfma_f32_16x16x32_bf16 v[82:85], v[156:159], v[214:217], v[82:85]
	s_setprio 0
	s_setprio 1
	v_mfma_f32_16x16x32_bf16 v[62:65], v[160:163], v[176:179], 0
	v_mfma_f32_16x16x32_bf16 v[30:33], v[168:171], v[176:179], 0
	v_mfma_f32_16x16x32_bf16 v[58:61], v[160:163], v[184:187], 0
	v_mfma_f32_16x16x32_bf16 v[26:29], v[168:171], v[184:187], 0
	v_mfma_f32_16x16x32_bf16 v[54:57], v[160:163], v[192:195], 0
	v_mfma_f32_16x16x32_bf16 v[22:25], v[168:171], v[192:195], 0
	v_mfma_f32_16x16x32_bf16 v[50:53], v[160:163], v[200:203], 0
	v_mfma_f32_16x16x32_bf16 v[18:21], v[168:171], v[200:203], 0
	v_mfma_f32_16x16x32_bf16 v[62:65], v[164:167], v[180:183], v[62:65]
	v_mfma_f32_16x16x32_bf16 v[30:33], v[172:175], v[180:183], v[30:33]
	v_mfma_f32_16x16x32_bf16 v[58:61], v[164:167], v[188:191], v[58:61]
	v_mfma_f32_16x16x32_bf16 v[26:29], v[172:175], v[188:191], v[26:29]
	v_mfma_f32_16x16x32_bf16 v[54:57], v[164:167], v[196:199], v[54:57]
	v_mfma_f32_16x16x32_bf16 v[22:25], v[172:175], v[196:199], v[22:25]
	v_mfma_f32_16x16x32_bf16 v[50:53], v[164:167], v[214:217], v[50:53]
	v_mfma_f32_16x16x32_bf16 v[18:21], v[172:175], v[214:217], v[18:21]
	s_setprio 0
	s_barrier
	s_add_i32 s89, s89, s56
	v_lshl_add_u64 v[146:147], s[62:63], 0, v[132:133]
	s_mov_b32 m0, s89
	ds_read_b128 v[176:179], v150 offset:16384
	ds_read_b128 v[180:183], v150 offset:17408
	ds_read_b128 v[184:187], v150 offset:18432
	ds_read_b128 v[188:191], v150 offset:19456
	ds_read_b128 v[192:195], v150 offset:20480
	ds_read_b128 v[196:199], v150 offset:21504
	ds_read_b128 v[200:203], v150 offset:22528
	ds_read_b128 v[214:217], v150 offset:23552
	global_load_lds_dwordx4 v[146:147], off
	s_add_i32 m0, s89, 0x2000
	v_lshl_add_u64 v[204:205], s[62:63], 0, v[130:131]
	s_add_u32 s62, s62, s8
	s_addc_u32 s63, s63, s9
	s_add_i32 s31, s31, s56
	global_load_lds_dwordx4 v[204:205], off
	v_lshl_add_u64 v[218:219], s[62:63], 0, v[132:133]
	s_mov_b32 m0, s31
	v_lshl_add_u64 v[220:221], s[62:63], 0, v[130:131]
	global_load_lds_dwordx4 v[218:219], off
	s_add_i32 m0, s31, 0x2000
	v_lshl_add_u64 v[222:223], s[22:23], 0, v[132:133]
	global_load_lds_dwordx4 v[220:221], off
	s_mov_b32 m0, s67
	v_lshl_add_u64 v[224:225], s[22:23], 0, v[130:131]
	global_load_lds_dwordx4 v[222:223], off
	s_mov_b32 m0, s72
	s_nop 0
	global_load_lds_dwordx4 v[224:225], off
	s_waitcnt vmcnt(8)
	s_waitcnt lgkmcnt(0)
	s_barrier
	s_setprio 1
	s_waitcnt lgkmcnt(0)
	v_mfma_f32_16x16x32_bf16 v[110:113], v[138:141], v[176:179], 0
	v_mfma_f32_16x16x32_bf16 v[78:81], v[152:155], v[176:179], 0
	v_mfma_f32_16x16x32_bf16 v[106:109], v[138:141], v[184:187], 0
	v_mfma_f32_16x16x32_bf16 v[74:77], v[152:155], v[184:187], 0
	v_mfma_f32_16x16x32_bf16 v[102:105], v[138:141], v[192:195], 0
	v_mfma_f32_16x16x32_bf16 v[70:73], v[152:155], v[192:195], 0
	v_mfma_f32_16x16x32_bf16 v[98:101], v[138:141], v[200:203], 0
	v_mfma_f32_16x16x32_bf16 v[66:69], v[152:155], v[200:203], 0
	v_mfma_f32_16x16x32_bf16 v[110:113], v[142:145], v[180:183], v[110:113]
	v_mfma_f32_16x16x32_bf16 v[78:81], v[156:159], v[180:183], v[78:81]
	v_mfma_f32_16x16x32_bf16 v[106:109], v[142:145], v[188:191], v[106:109]
	v_mfma_f32_16x16x32_bf16 v[74:77], v[156:159], v[188:191], v[74:77]
	v_mfma_f32_16x16x32_bf16 v[102:105], v[142:145], v[196:199], v[102:105]
	v_mfma_f32_16x16x32_bf16 v[70:73], v[156:159], v[196:199], v[70:73]
	v_mfma_f32_16x16x32_bf16 v[98:101], v[142:145], v[214:217], v[98:101]
	v_mfma_f32_16x16x32_bf16 v[66:69], v[156:159], v[214:217], v[66:69]
	s_setprio 0
	s_setprio 1
	v_mfma_f32_16x16x32_bf16 v[46:49], v[160:163], v[176:179], 0
	v_mfma_f32_16x16x32_bf16 v[14:17], v[168:171], v[176:179], 0
	v_mfma_f32_16x16x32_bf16 v[42:45], v[160:163], v[184:187], 0
	v_mfma_f32_16x16x32_bf16 v[10:13], v[168:171], v[184:187], 0
	v_mfma_f32_16x16x32_bf16 v[38:41], v[160:163], v[192:195], 0
	v_mfma_f32_16x16x32_bf16 v[6:9], v[168:171], v[192:195], 0
	v_mfma_f32_16x16x32_bf16 v[34:37], v[160:163], v[200:203], 0
	v_mfma_f32_16x16x32_bf16 v[2:5], v[168:171], v[200:203], 0
	v_mfma_f32_16x16x32_bf16 v[46:49], v[164:167], v[180:183], v[46:49]
	v_mfma_f32_16x16x32_bf16 v[14:17], v[172:175], v[180:183], v[14:17]
	v_mfma_f32_16x16x32_bf16 v[42:45], v[164:167], v[188:191], v[42:45]
	v_mfma_f32_16x16x32_bf16 v[10:13], v[172:175], v[188:191], v[10:13]
	v_mfma_f32_16x16x32_bf16 v[38:41], v[164:167], v[196:199], v[38:41]
	v_mfma_f32_16x16x32_bf16 v[6:9], v[172:175], v[196:199], v[6:9]
	v_mfma_f32_16x16x32_bf16 v[34:37], v[164:167], v[214:217], v[34:37]
	v_mfma_f32_16x16x32_bf16 v[2:5], v[172:175], v[214:217], v[2:5]
	s_setprio 0
	s_barrier
	s_add_i32 s31, 0, 0x18000
	v_add_u32_e32 v151, s31, v148
	s_add_i32 s62, 0, 0x1c000
	ds_read_b128 v[138:141], v151
	ds_read_b128 v[142:145], v151 offset:1024
	ds_read_b128 v[152:155], v151 offset:2048
	ds_read_b128 v[156:159], v151 offset:3072
	v_add_u32_e32 v151, s62, v148
	ds_read_b128 v[160:163], v151
	ds_read_b128 v[164:167], v151 offset:1024
	ds_read_b128 v[168:171], v151 offset:2048
	ds_read_b128 v[172:175], v151 offset:3072
	s_add_u32 s22, s22, s8
	s_addc_u32 s23, s23, s9
	s_mov_b32 m0, s73
	v_lshl_add_u64 v[226:227], s[22:23], 0, v[132:133]
	ds_read_b128 v[176:179], v150 offset:32768
	ds_read_b128 v[180:183], v150 offset:33792
	ds_read_b128 v[184:187], v150 offset:34816
	ds_read_b128 v[188:191], v150 offset:35840
	ds_read_b128 v[192:195], v150 offset:36864
	ds_read_b128 v[196:199], v150 offset:37888
	ds_read_b128 v[200:203], v150 offset:38912
	ds_read_b128 v[214:217], v150 offset:39936
	global_load_lds_dwordx4 v[226:227], off
	v_lshl_add_u64 v[226:227], s[22:23], 0, v[130:131]
	s_mov_b32 m0, s74
	s_nop 0
	global_load_lds_dwordx4 v[226:227], off
	s_waitcnt vmcnt(8)
	s_waitcnt lgkmcnt(0)
	s_barrier
	s_setprio 1
	s_waitcnt lgkmcnt(0)
	v_mfma_f32_16x16x32_bf16 v[126:129], v[138:141], v[176:179], v[126:129]
	v_mfma_f32_16x16x32_bf16 v[94:97], v[152:155], v[176:179], v[94:97]
	v_mfma_f32_16x16x32_bf16 v[122:125], v[138:141], v[184:187], v[122:125]
	v_mfma_f32_16x16x32_bf16 v[90:93], v[152:155], v[184:187], v[90:93]
	v_mfma_f32_16x16x32_bf16 v[118:121], v[138:141], v[192:195], v[118:121]
	v_mfma_f32_16x16x32_bf16 v[86:89], v[152:155], v[192:195], v[86:89]
	v_mfma_f32_16x16x32_bf16 v[114:117], v[138:141], v[200:203], v[114:117]
	v_mfma_f32_16x16x32_bf16 v[82:85], v[152:155], v[200:203], v[82:85]
	v_mfma_f32_16x16x32_bf16 v[126:129], v[142:145], v[180:183], v[126:129]
	v_mfma_f32_16x16x32_bf16 v[94:97], v[156:159], v[180:183], v[94:97]
	v_mfma_f32_16x16x32_bf16 v[122:125], v[142:145], v[188:191], v[122:125]
	v_mfma_f32_16x16x32_bf16 v[90:93], v[156:159], v[188:191], v[90:93]
	v_mfma_f32_16x16x32_bf16 v[118:121], v[142:145], v[196:199], v[118:121]
	v_mfma_f32_16x16x32_bf16 v[86:89], v[156:159], v[196:199], v[86:89]
	v_mfma_f32_16x16x32_bf16 v[114:117], v[142:145], v[214:217], v[114:117]
	v_mfma_f32_16x16x32_bf16 v[82:85], v[156:159], v[214:217], v[82:85]
	s_setprio 0
	s_setprio 1
	v_mfma_f32_16x16x32_bf16 v[62:65], v[160:163], v[176:179], v[62:65]
	v_mfma_f32_16x16x32_bf16 v[30:33], v[168:171], v[176:179], v[30:33]
	v_mfma_f32_16x16x32_bf16 v[58:61], v[160:163], v[184:187], v[58:61]
	v_mfma_f32_16x16x32_bf16 v[26:29], v[168:171], v[184:187], v[26:29]
	v_mfma_f32_16x16x32_bf16 v[54:57], v[160:163], v[192:195], v[54:57]
	v_mfma_f32_16x16x32_bf16 v[22:25], v[168:171], v[192:195], v[22:25]
	v_mfma_f32_16x16x32_bf16 v[50:53], v[160:163], v[200:203], v[50:53]
	v_mfma_f32_16x16x32_bf16 v[18:21], v[168:171], v[200:203], v[18:21]
	v_mfma_f32_16x16x32_bf16 v[62:65], v[164:167], v[180:183], v[62:65]
	v_mfma_f32_16x16x32_bf16 v[30:33], v[172:175], v[180:183], v[30:33]
	v_mfma_f32_16x16x32_bf16 v[58:61], v[164:167], v[188:191], v[58:61]
	v_mfma_f32_16x16x32_bf16 v[26:29], v[172:175], v[188:191], v[26:29]
	v_mfma_f32_16x16x32_bf16 v[54:57], v[164:167], v[196:199], v[54:57]
	v_mfma_f32_16x16x32_bf16 v[22:25], v[172:175], v[196:199], v[22:25]
	v_mfma_f32_16x16x32_bf16 v[50:53], v[164:167], v[214:217], v[50:53]
	v_mfma_f32_16x16x32_bf16 v[18:21], v[172:175], v[214:217], v[18:21]
	s_setprio 0
	s_barrier
	s_add_i32 s22, s31, s56
	v_lshl_add_u64 v[146:147], v[146:147], 0, s[60:61]
	s_mov_b32 m0, s22
	ds_read_b128 v[176:179], v150 offset:49152
	ds_read_b128 v[180:183], v150 offset:50176
	ds_read_b128 v[184:187], v150 offset:51200
	ds_read_b128 v[188:191], v150 offset:52224
	ds_read_b128 v[192:195], v150 offset:53248
	ds_read_b128 v[196:199], v150 offset:54272
	ds_read_b128 v[200:203], v150 offset:55296
	ds_read_b128 v[214:217], v150 offset:56320
	global_load_lds_dwordx4 v[146:147], off
	v_lshl_add_u64 v[146:147], v[204:205], 0, s[60:61]
	s_add_i32 m0, s22, 0x2000
	s_add_i32 s22, s62, s56
	global_load_lds_dwordx4 v[146:147], off
	v_lshl_add_u64 v[146:147], v[218:219], 0, s[60:61]
	s_mov_b32 m0, s22
	s_nop 0
	global_load_lds_dwordx4 v[146:147], off
	v_lshl_add_u64 v[146:147], v[220:221], 0, s[60:61]
	s_add_i32 m0, s22, 0x2000
	s_nop 0
	global_load_lds_dwordx4 v[146:147], off
	v_lshl_add_u64 v[146:147], v[222:223], 0, s[60:61]
	s_mov_b32 m0, s77
	s_nop 0
	global_load_lds_dwordx4 v[146:147], off
	v_lshl_add_u64 v[146:147], v[224:225], 0, s[60:61]
	s_mov_b32 m0, s78
	s_nop 0
	global_load_lds_dwordx4 v[146:147], off
	s_waitcnt vmcnt(8)
	s_waitcnt lgkmcnt(0)
	s_barrier
	s_setprio 1
	s_waitcnt lgkmcnt(0)
	v_mfma_f32_16x16x32_bf16 v[110:113], v[138:141], v[176:179], v[110:113]
	v_mfma_f32_16x16x32_bf16 v[78:81], v[152:155], v[176:179], v[78:81]
	v_mfma_f32_16x16x32_bf16 v[106:109], v[138:141], v[184:187], v[106:109]
	v_mfma_f32_16x16x32_bf16 v[74:77], v[152:155], v[184:187], v[74:77]
	v_mfma_f32_16x16x32_bf16 v[102:105], v[138:141], v[192:195], v[102:105]
	v_mfma_f32_16x16x32_bf16 v[70:73], v[152:155], v[192:195], v[70:73]
	v_mfma_f32_16x16x32_bf16 v[98:101], v[138:141], v[200:203], v[98:101]
	v_mfma_f32_16x16x32_bf16 v[66:69], v[152:155], v[200:203], v[66:69]
	v_mfma_f32_16x16x32_bf16 v[110:113], v[142:145], v[180:183], v[110:113]
	v_mfma_f32_16x16x32_bf16 v[78:81], v[156:159], v[180:183], v[78:81]
	v_mfma_f32_16x16x32_bf16 v[106:109], v[142:145], v[188:191], v[106:109]
	v_mfma_f32_16x16x32_bf16 v[74:77], v[156:159], v[188:191], v[74:77]
	v_mfma_f32_16x16x32_bf16 v[102:105], v[142:145], v[196:199], v[102:105]
	v_mfma_f32_16x16x32_bf16 v[70:73], v[156:159], v[196:199], v[70:73]
	v_mfma_f32_16x16x32_bf16 v[98:101], v[142:145], v[214:217], v[98:101]
	v_mfma_f32_16x16x32_bf16 v[66:69], v[156:159], v[214:217], v[66:69]
	s_setprio 0
	s_setprio 1
	v_mfma_f32_16x16x32_bf16 v[46:49], v[160:163], v[176:179], v[46:49]
	v_mfma_f32_16x16x32_bf16 v[14:17], v[168:171], v[176:179], v[14:17]
	v_mfma_f32_16x16x32_bf16 v[42:45], v[160:163], v[184:187], v[42:45]
	v_mfma_f32_16x16x32_bf16 v[10:13], v[168:171], v[184:187], v[10:13]
	v_mfma_f32_16x16x32_bf16 v[38:41], v[160:163], v[192:195], v[38:41]
	v_mfma_f32_16x16x32_bf16 v[6:9], v[168:171], v[192:195], v[6:9]
	v_mfma_f32_16x16x32_bf16 v[34:37], v[160:163], v[200:203], v[34:37]
	v_mfma_f32_16x16x32_bf16 v[2:5], v[168:171], v[200:203], v[2:5]
	v_mfma_f32_16x16x32_bf16 v[46:49], v[164:167], v[180:183], v[46:49]
	v_mfma_f32_16x16x32_bf16 v[14:17], v[172:175], v[180:183], v[14:17]
	v_mfma_f32_16x16x32_bf16 v[42:45], v[164:167], v[188:191], v[42:45]
	v_mfma_f32_16x16x32_bf16 v[10:13], v[172:175], v[188:191], v[10:13]
	v_mfma_f32_16x16x32_bf16 v[38:41], v[164:167], v[196:199], v[38:41]
	v_mfma_f32_16x16x32_bf16 v[6:9], v[172:175], v[196:199], v[6:9]
	v_mfma_f32_16x16x32_bf16 v[34:37], v[164:167], v[214:217], v[34:37]
	v_mfma_f32_16x16x32_bf16 v[2:5], v[172:175], v[214:217], v[2:5]
	s_setprio 0
	s_barrier
	s_add_u32 s20, s20, 0x100
	s_addc_u32 s21, s21, 0
	s_add_u32 vcc_lo, vcc_lo, 0x100
	s_addc_u32 vcc_hi, vcc_hi, 0
	s_cmp_ge_i32 s88, s79
	s_mov_b32 s22, s88
	s_cbranch_scc1 .LBB0_361

.Lzgo_3:
	s_add_u32 s18, s18, 0x80
	s_addc_u32 s19, s19, 0
	s_add_u32 s71, s20, 0x100
	s_addc_u32 s72, s21, 0
	s_mov_b32 s20, 0
	s_add_i32 s73, s20, 2
	s_add_u32 s31, s18, 0x80
	s_addc_u32 s21, s19, 0
	s_add_i32 s74, 0, 0x10000
	s_cmp_eq_u32 s11, s20
	s_cselect_b32 s21, s3, s21
	s_cselect_b32 s20, s2, s31
	v_add_u32_e32 v145, s74, v142
	s_cselect_b32 s63, s17, s72
	s_cselect_b32 s62, s16, s71
	s_add_i32 s31, 0, 0x14000
	ds_read_b128 v[146:149], v145
	ds_read_b128 v[150:153], v145 offset:1024
	ds_read_b128 v[154:157], v145 offset:2048
	ds_read_b128 v[158:161], v145 offset:3072
	v_add_u32_e32 v145, s31, v142
	ds_read_b128 v[162:165], v145
	ds_read_b128 v[166:169], v145 offset:1024
	ds_read_b128 v[170:173], v145 offset:2048
	ds_read_b128 v[174:177], v145 offset:3072
	v_lshl_add_u64 v[218:219], s[18:19], 0, v[138:139]
	s_add_i32 m0, s23, 0xc000
	ds_read_b128 v[178:181], v144
	ds_read_b128 v[182:185], v144 offset:1024
	ds_read_b128 v[186:189], v144 offset:2048
	ds_read_b128 v[190:193], v144 offset:3072
	ds_read_b128 v[194:197], v144 offset:4096
	ds_read_b128 v[198:201], v144 offset:5120
	ds_read_b128 v[202:205], v144 offset:6144
	ds_read_b128 v[214:217], v144 offset:7168
	global_load_lds_dwordx4 v[218:219], off
	v_lshl_add_u64 v[218:219], s[18:19], 0, v[140:141]
	s_add_i32 m0, s23, 0xe000
	s_nop 0
	global_load_lds_dwordx4 v[218:219], off
	s_waitcnt vmcnt(8)
	s_waitcnt lgkmcnt(0)
	s_barrier
	s_setprio 1
	s_waitcnt lgkmcnt(0)
	v_mfma_f32_16x16x32_bf16 v[122:125], v[146:149], v[178:181], 0
	v_mfma_f32_16x16x32_bf16 v[126:129], v[154:157], v[178:181], 0
	v_mfma_f32_16x16x32_bf16 v[118:121], v[146:149], v[186:189], 0
	v_mfma_f32_16x16x32_bf16 v[114:117], v[154:157], v[186:189], 0
	v_mfma_f32_16x16x32_bf16 v[110:113], v[146:149], v[194:197], 0
	v_mfma_f32_16x16x32_bf16 v[106:109], v[154:157], v[194:197], 0
	v_mfma_f32_16x16x32_bf16 v[102:105], v[146:149], v[202:205], 0
	v_mfma_f32_16x16x32_bf16 v[98:101], v[154:157], v[202:205], 0
	v_mfma_f32_16x16x32_bf16 v[122:125], v[150:153], v[182:185], v[122:125]
	v_mfma_f32_16x16x32_bf16 v[126:129], v[158:161], v[182:185], v[126:129]
	v_mfma_f32_16x16x32_bf16 v[118:121], v[150:153], v[190:193], v[118:121]
	v_mfma_f32_16x16x32_bf16 v[114:117], v[158:161], v[190:193], v[114:117]
	v_mfma_f32_16x16x32_bf16 v[110:113], v[150:153], v[198:201], v[110:113]
	v_mfma_f32_16x16x32_bf16 v[106:109], v[158:161], v[198:201], v[106:109]
	v_mfma_f32_16x16x32_bf16 v[102:105], v[150:153], v[214:217], v[102:105]
	v_mfma_f32_16x16x32_bf16 v[98:101], v[158:161], v[214:217], v[98:101]
	s_setprio 0
	s_setprio 1
	v_mfma_f32_16x16x32_bf16 v[62:65], v[162:165], v[178:181], 0
	v_mfma_f32_16x16x32_bf16 v[58:61], v[170:173], v[178:181], 0
	v_mfma_f32_16x16x32_bf16 v[54:57], v[162:165], v[186:189], 0
	v_mfma_f32_16x16x32_bf16 v[50:53], v[170:173], v[186:189], 0
	v_mfma_f32_16x16x32_bf16 v[46:49], v[162:165], v[194:197], 0
	v_mfma_f32_16x16x32_bf16 v[42:45], v[170:173], v[194:197], 0
	v_mfma_f32_16x16x32_bf16 v[38:41], v[162:165], v[202:205], 0
	v_mfma_f32_16x16x32_bf16 v[34:37], v[170:173], v[202:205], 0
	v_mfma_f32_16x16x32_bf16 v[62:65], v[166:169], v[182:185], v[62:65]
	v_mfma_f32_16x16x32_bf16 v[58:61], v[174:177], v[182:185], v[58:61]
	v_mfma_f32_16x16x32_bf16 v[54:57], v[166:169], v[190:193], v[54:57]
	v_mfma_f32_16x16x32_bf16 v[50:53], v[174:177], v[190:193], v[50:53]
	v_mfma_f32_16x16x32_bf16 v[46:49], v[166:169], v[198:201], v[46:49]
	v_mfma_f32_16x16x32_bf16 v[42:45], v[174:177], v[198:201], v[42:45]
	v_mfma_f32_16x16x32_bf16 v[38:41], v[166:169], v[214:217], v[38:41]
	v_mfma_f32_16x16x32_bf16 v[34:37], v[174:177], v[214:217], v[34:37]
	s_setprio 0
	s_barrier
	s_add_i32 s74, s74, s22
	v_lshl_add_u64 v[218:219], s[62:63], 0, v[134:135]
	s_mov_b32 m0, s74
	ds_read_b128 v[178:181], v144 offset:16384
	ds_read_b128 v[182:185], v144 offset:17408
	ds_read_b128 v[186:189], v144 offset:18432
	ds_read_b128 v[190:193], v144 offset:19456
	ds_read_b128 v[194:197], v144 offset:20480
	ds_read_b128 v[198:201], v144 offset:21504
	ds_read_b128 v[202:205], v144 offset:22528
	ds_read_b128 v[214:217], v144 offset:23552
	global_load_lds_dwordx4 v[218:219], off
	s_add_i32 m0, s74, 0x2000
	v_lshl_add_u64 v[220:221], s[62:63], 0, v[130:131]
	s_add_u32 s62, s62, s4
	s_addc_u32 s63, s63, s5
	s_add_i32 s31, s31, s22
	global_load_lds_dwordx4 v[220:221], off
	v_lshl_add_u64 v[222:223], s[62:63], 0, v[134:135]
	s_mov_b32 m0, s31
	v_lshl_add_u64 v[224:225], s[62:63], 0, v[130:131]
	global_load_lds_dwordx4 v[222:223], off
	s_add_i32 m0, s31, 0x2000
	v_lshl_add_u64 v[226:227], s[20:21], 0, v[136:137]
	global_load_lds_dwordx4 v[224:225], off
	s_mov_b32 m0, s23
	v_lshl_add_u64 v[236:237], s[20:21], 0, v[132:133]
	global_load_lds_dwordx4 v[226:227], off
	s_mov_b32 m0, s52
	s_nop 0
	global_load_lds_dwordx4 v[236:237], off
	s_waitcnt vmcnt(8)
	s_waitcnt lgkmcnt(0)
	s_barrier
	s_setprio 1
	s_waitcnt lgkmcnt(0)
	v_mfma_f32_16x16x32_bf16 v[94:97], v[146:149], v[178:181], 0
	v_mfma_f32_16x16x32_bf16 v[90:93], v[154:157], v[178:181], 0
	v_mfma_f32_16x16x32_bf16 v[86:89], v[146:149], v[186:189], 0
	v_mfma_f32_16x16x32_bf16 v[82:85], v[154:157], v[186:189], 0
	v_mfma_f32_16x16x32_bf16 v[78:81], v[146:149], v[194:197], 0
	v_mfma_f32_16x16x32_bf16 v[74:77], v[154:157], v[194:197], 0
	v_mfma_f32_16x16x32_bf16 v[70:73], v[146:149], v[202:205], 0
	v_mfma_f32_16x16x32_bf16 v[66:69], v[154:157], v[202:205], 0
	v_mfma_f32_16x16x32_bf16 v[94:97], v[150:153], v[182:185], v[94:97]
	v_mfma_f32_16x16x32_bf16 v[90:93], v[158:161], v[182:185], v[90:93]
	v_mfma_f32_16x16x32_bf16 v[86:89], v[150:153], v[190:193], v[86:89]
	v_mfma_f32_16x16x32_bf16 v[82:85], v[158:161], v[190:193], v[82:85]
	v_mfma_f32_16x16x32_bf16 v[78:81], v[150:153], v[198:201], v[78:81]
	v_mfma_f32_16x16x32_bf16 v[74:77], v[158:161], v[198:201], v[74:77]
	v_mfma_f32_16x16x32_bf16 v[70:73], v[150:153], v[214:217], v[70:73]
	v_mfma_f32_16x16x32_bf16 v[66:69], v[158:161], v[214:217], v[66:69]
	s_setprio 0
	s_setprio 1
	v_mfma_f32_16x16x32_bf16 v[30:33], v[162:165], v[178:181], 0
	v_mfma_f32_16x16x32_bf16 v[26:29], v[170:173], v[178:181], 0
	v_mfma_f32_16x16x32_bf16 v[22:25], v[162:165], v[186:189], 0
	v_mfma_f32_16x16x32_bf16 v[18:21], v[170:173], v[186:189], 0
	v_mfma_f32_16x16x32_bf16 v[14:17], v[162:165], v[194:197], 0
	v_mfma_f32_16x16x32_bf16 v[10:13], v[170:173], v[194:197], 0
	v_mfma_f32_16x16x32_bf16 v[6:9], v[162:165], v[202:205], 0
	v_mfma_f32_16x16x32_bf16 v[2:5], v[170:173], v[202:205], 0
	v_mfma_f32_16x16x32_bf16 v[30:33], v[166:169], v[182:185], v[30:33]
	v_mfma_f32_16x16x32_bf16 v[26:29], v[174:177], v[182:185], v[26:29]
	v_mfma_f32_16x16x32_bf16 v[22:25], v[166:169], v[190:193], v[22:25]
	v_mfma_f32_16x16x32_bf16 v[18:21], v[174:177], v[190:193], v[18:21]
	v_mfma_f32_16x16x32_bf16 v[14:17], v[166:169], v[198:201], v[14:17]
	v_mfma_f32_16x16x32_bf16 v[10:13], v[174:177], v[198:201], v[10:13]
	v_mfma_f32_16x16x32_bf16 v[6:9], v[166:169], v[214:217], v[6:9]
	v_mfma_f32_16x16x32_bf16 v[2:5], v[174:177], v[214:217], v[2:5]
	s_setprio 0
	s_barrier
	s_add_i32 s31, 0, 0x18000
	v_add_u32_e32 v145, s31, v142
	s_add_i32 s62, 0, 0x1c000
	ds_read_b128 v[146:149], v145
	ds_read_b128 v[150:153], v145 offset:1024
	ds_read_b128 v[154:157], v145 offset:2048
	ds_read_b128 v[158:161], v145 offset:3072
	v_add_u32_e32 v145, s62, v142
	ds_read_b128 v[162:165], v145
	ds_read_b128 v[166:169], v145 offset:1024
	ds_read_b128 v[170:173], v145 offset:2048
	ds_read_b128 v[174:177], v145 offset:3072
	s_add_u32 s20, s20, s4
	s_addc_u32 s21, s21, s5
	s_mov_b32 m0, s53
	v_lshl_add_u64 v[238:239], s[20:21], 0, v[136:137]
	ds_read_b128 v[178:181], v144 offset:32768
	ds_read_b128 v[182:185], v144 offset:33792
	ds_read_b128 v[186:189], v144 offset:34816
	ds_read_b128 v[190:193], v144 offset:35840
	ds_read_b128 v[194:197], v144 offset:36864
	ds_read_b128 v[198:201], v144 offset:37888
	ds_read_b128 v[202:205], v144 offset:38912
	ds_read_b128 v[214:217], v144 offset:39936
	global_load_lds_dwordx4 v[238:239], off
	v_lshl_add_u64 v[238:239], s[20:21], 0, v[132:133]
	s_mov_b32 m0, s56
	s_nop 0
	global_load_lds_dwordx4 v[238:239], off
	s_waitcnt vmcnt(8)
	s_waitcnt lgkmcnt(0)
	s_barrier
	s_setprio 1
	s_waitcnt lgkmcnt(0)
	v_mfma_f32_16x16x32_bf16 v[122:125], v[146:149], v[178:181], v[122:125]
	v_mfma_f32_16x16x32_bf16 v[126:129], v[154:157], v[178:181], v[126:129]
	v_mfma_f32_16x16x32_bf16 v[118:121], v[146:149], v[186:189], v[118:121]
	v_mfma_f32_16x16x32_bf16 v[114:117], v[154:157], v[186:189], v[114:117]
	v_mfma_f32_16x16x32_bf16 v[110:113], v[146:149], v[194:197], v[110:113]
	v_mfma_f32_16x16x32_bf16 v[106:109], v[154:157], v[194:197], v[106:109]
	v_mfma_f32_16x16x32_bf16 v[102:105], v[146:149], v[202:205], v[102:105]
	v_mfma_f32_16x16x32_bf16 v[98:101], v[154:157], v[202:205], v[98:101]
	v_mfma_f32_16x16x32_bf16 v[122:125], v[150:153], v[182:185], v[122:125]
	v_mfma_f32_16x16x32_bf16 v[126:129], v[158:161], v[182:185], v[126:129]
	v_mfma_f32_16x16x32_bf16 v[118:121], v[150:153], v[190:193], v[118:121]
	v_mfma_f32_16x16x32_bf16 v[114:117], v[158:161], v[190:193], v[114:117]
	v_mfma_f32_16x16x32_bf16 v[110:113], v[150:153], v[198:201], v[110:113]
	v_mfma_f32_16x16x32_bf16 v[106:109], v[158:161], v[198:201], v[106:109]
	v_mfma_f32_16x16x32_bf16 v[102:105], v[150:153], v[214:217], v[102:105]
	v_mfma_f32_16x16x32_bf16 v[98:101], v[158:161], v[214:217], v[98:101]
	s_setprio 0
	s_setprio 1
	v_mfma_f32_16x16x32_bf16 v[62:65], v[162:165], v[178:181], v[62:65]
	v_mfma_f32_16x16x32_bf16 v[58:61], v[170:173], v[178:181], v[58:61]
	v_mfma_f32_16x16x32_bf16 v[54:57], v[162:165], v[186:189], v[54:57]
	v_mfma_f32_16x16x32_bf16 v[50:53], v[170:173], v[186:189], v[50:53]
	v_mfma_f32_16x16x32_bf16 v[46:49], v[162:165], v[194:197], v[46:49]
	v_mfma_f32_16x16x32_bf16 v[42:45], v[170:173], v[194:197], v[42:45]
	v_mfma_f32_16x16x32_bf16 v[38:41], v[162:165], v[202:205], v[38:41]
	v_mfma_f32_16x16x32_bf16 v[34:37], v[170:173], v[202:205], v[34:37]
	v_mfma_f32_16x16x32_bf16 v[62:65], v[166:169], v[182:185], v[62:65]
	v_mfma_f32_16x16x32_bf16 v[58:61], v[174:177], v[182:185], v[58:61]
	v_mfma_f32_16x16x32_bf16 v[54:57], v[166:169], v[190:193], v[54:57]
	v_mfma_f32_16x16x32_bf16 v[50:53], v[174:177], v[190:193], v[50:53]
	v_mfma_f32_16x16x32_bf16 v[46:49], v[166:169], v[198:201], v[46:49]
	v_mfma_f32_16x16x32_bf16 v[42:45], v[174:177], v[198:201], v[42:45]
	v_mfma_f32_16x16x32_bf16 v[38:41], v[166:169], v[214:217], v[38:41]
	v_mfma_f32_16x16x32_bf16 v[34:37], v[174:177], v[214:217], v[34:37]
	s_setprio 0
	s_barrier
	s_add_i32 s20, s31, s22
	v_lshl_add_u64 v[218:219], v[218:219], 0, s[60:61]
	s_mov_b32 m0, s20
	ds_read_b128 v[178:181], v144 offset:49152
	ds_read_b128 v[182:185], v144 offset:50176
	ds_read_b128 v[186:189], v144 offset:51200
	ds_read_b128 v[190:193], v144 offset:52224
	ds_read_b128 v[194:197], v144 offset:53248
	ds_read_b128 v[198:201], v144 offset:54272
	ds_read_b128 v[202:205], v144 offset:55296
	ds_read_b128 v[214:217], v144 offset:56320
	global_load_lds_dwordx4 v[218:219], off
	v_lshl_add_u64 v[218:219], v[220:221], 0, s[60:61]
	s_add_i32 m0, s20, 0x2000
	s_add_i32 s20, s62, s22
	global_load_lds_dwordx4 v[218:219], off
	v_lshl_add_u64 v[218:219], v[222:223], 0, s[60:61]
	s_mov_b32 m0, s20
	s_nop 0
	global_load_lds_dwordx4 v[218:219], off
	v_lshl_add_u64 v[218:219], v[224:225], 0, s[60:61]
	s_add_i32 m0, s20, 0x2000
	s_nop 0
	global_load_lds_dwordx4 v[218:219], off
	v_lshl_add_u64 v[218:219], v[226:227], 0, s[60:61]
	s_mov_b32 m0, s57
	s_nop 0
	global_load_lds_dwordx4 v[218:219], off
	v_lshl_add_u64 v[218:219], v[236:237], 0, s[60:61]
	s_mov_b32 m0, s65
	s_nop 0
	global_load_lds_dwordx4 v[218:219], off
	s_waitcnt vmcnt(8)
	s_waitcnt lgkmcnt(0)
	s_barrier
	s_setprio 1
	s_waitcnt lgkmcnt(0)
	v_mfma_f32_16x16x32_bf16 v[94:97], v[146:149], v[178:181], v[94:97]
	v_mfma_f32_16x16x32_bf16 v[90:93], v[154:157], v[178:181], v[90:93]
	v_mfma_f32_16x16x32_bf16 v[86:89], v[146:149], v[186:189], v[86:89]
	v_mfma_f32_16x16x32_bf16 v[82:85], v[154:157], v[186:189], v[82:85]
	v_mfma_f32_16x16x32_bf16 v[78:81], v[146:149], v[194:197], v[78:81]
	v_mfma_f32_16x16x32_bf16 v[74:77], v[154:157], v[194:197], v[74:77]
	v_mfma_f32_16x16x32_bf16 v[70:73], v[146:149], v[202:205], v[70:73]
	v_mfma_f32_16x16x32_bf16 v[66:69], v[154:157], v[202:205], v[66:69]
	v_mfma_f32_16x16x32_bf16 v[94:97], v[150:153], v[182:185], v[94:97]
	v_mfma_f32_16x16x32_bf16 v[90:93], v[158:161], v[182:185], v[90:93]
	v_mfma_f32_16x16x32_bf16 v[86:89], v[150:153], v[190:193], v[86:89]
	v_mfma_f32_16x16x32_bf16 v[82:85], v[158:161], v[190:193], v[82:85]
	v_mfma_f32_16x16x32_bf16 v[78:81], v[150:153], v[198:201], v[78:81]
	v_mfma_f32_16x16x32_bf16 v[74:77], v[158:161], v[198:201], v[74:77]
	v_mfma_f32_16x16x32_bf16 v[70:73], v[150:153], v[214:217], v[70:73]
	v_mfma_f32_16x16x32_bf16 v[66:69], v[158:161], v[214:217], v[66:69]
	s_setprio 0
	s_setprio 1
	v_mfma_f32_16x16x32_bf16 v[30:33], v[162:165], v[178:181], v[30:33]
	v_mfma_f32_16x16x32_bf16 v[26:29], v[170:173], v[178:181], v[26:29]
	v_mfma_f32_16x16x32_bf16 v[22:25], v[162:165], v[186:189], v[22:25]
	v_mfma_f32_16x16x32_bf16 v[18:21], v[170:173], v[186:189], v[18:21]
	v_mfma_f32_16x16x32_bf16 v[14:17], v[162:165], v[194:197], v[14:17]
	v_mfma_f32_16x16x32_bf16 v[10:13], v[170:173], v[194:197], v[10:13]
	v_mfma_f32_16x16x32_bf16 v[6:9], v[162:165], v[202:205], v[6:9]
	v_mfma_f32_16x16x32_bf16 v[2:5], v[170:173], v[202:205], v[2:5]
	v_mfma_f32_16x16x32_bf16 v[30:33], v[166:169], v[182:185], v[30:33]
	v_mfma_f32_16x16x32_bf16 v[26:29], v[174:177], v[182:185], v[26:29]
	v_mfma_f32_16x16x32_bf16 v[22:25], v[166:169], v[190:193], v[22:25]
	v_mfma_f32_16x16x32_bf16 v[18:21], v[174:177], v[190:193], v[18:21]
	v_mfma_f32_16x16x32_bf16 v[14:17], v[166:169], v[198:201], v[14:17]
	v_mfma_f32_16x16x32_bf16 v[10:13], v[174:177], v[198:201], v[10:13]
	v_mfma_f32_16x16x32_bf16 v[6:9], v[166:169], v[214:217], v[6:9]
	v_mfma_f32_16x16x32_bf16 v[2:5], v[174:177], v[214:217], v[2:5]
	s_setprio 0
	s_barrier
	s_add_u32 s18, s18, 0x100
	s_addc_u32 s19, s19, 0
	s_add_u32 s71, s71, 0x100
	s_addc_u32 s72, s72, 0
	s_cmp_ge_i32 s73, s10
	s_mov_b32 s20, s73
	s_cbranch_scc1 .LBB0_493

.Lzgo_5:
	s_add_u32 s18, s18, 0x80
	s_addc_u32 s19, s19, 0
	s_add_u32 s71, s20, 0x100
	s_addc_u32 s72, s21, 0
	s_mov_b32 s20, 0
	s_add_i32 s73, s20, 2
	s_add_u32 s31, s18, 0x80
	s_addc_u32 s21, s19, 0
	s_add_i32 s74, 0, 0x10000
	s_cmp_eq_u32 s67, s20
	s_cselect_b32 s21, s3, s21
	s_cselect_b32 s20, s2, s31
	v_add_u32_e32 v149, s74, v146
	s_cselect_b32 s63, s17, s72
	s_cselect_b32 s62, s16, s71
	s_add_i32 s31, 0, 0x14000
	ds_read_b128 v[130:133], v149
	ds_read_b128 v[142:145], v149 offset:1024
	ds_read_b128 v[150:153], v149 offset:2048
	ds_read_b128 v[154:157], v149 offset:3072
	v_add_u32_e32 v149, s31, v146
	ds_read_b128 v[158:161], v149
	ds_read_b128 v[162:165], v149 offset:1024
	ds_read_b128 v[166:169], v149 offset:2048
	ds_read_b128 v[170:173], v149 offset:3072
	v_lshl_add_u64 v[214:215], s[18:19], 0, v[138:139]
	s_add_i32 m0, s23, 0xc000
	ds_read_b128 v[174:177], v148
	ds_read_b128 v[178:181], v148 offset:1024
	ds_read_b128 v[182:185], v148 offset:2048
	ds_read_b128 v[186:189], v148 offset:3072
	ds_read_b128 v[190:193], v148 offset:4096
	ds_read_b128 v[194:197], v148 offset:5120
	ds_read_b128 v[198:201], v148 offset:6144
	ds_read_b128 v[202:205], v148 offset:7168
	global_load_lds_dwordx4 v[214:215], off
	v_lshl_add_u64 v[214:215], s[18:19], 0, v[140:141]
	s_add_i32 m0, s23, 0xe000
	s_nop 0
	global_load_lds_dwordx4 v[214:215], off
	s_waitcnt vmcnt(8)
	s_waitcnt lgkmcnt(0)
	s_barrier
	s_setprio 1
	s_waitcnt lgkmcnt(0)
	v_mfma_f32_16x16x32_bf16 v[126:129], v[130:133], v[174:177], 0
	v_mfma_f32_16x16x32_bf16 v[94:97], v[150:153], v[174:177], 0
	v_mfma_f32_16x16x32_bf16 v[122:125], v[130:133], v[182:185], 0
	v_mfma_f32_16x16x32_bf16 v[90:93], v[150:153], v[182:185], 0
	v_mfma_f32_16x16x32_bf16 v[118:121], v[130:133], v[190:193], 0
	v_mfma_f32_16x16x32_bf16 v[86:89], v[150:153], v[190:193], 0
	v_mfma_f32_16x16x32_bf16 v[114:117], v[130:133], v[198:201], 0
	v_mfma_f32_16x16x32_bf16 v[82:85], v[150:153], v[198:201], 0
	v_mfma_f32_16x16x32_bf16 v[126:129], v[142:145], v[178:181], v[126:129]
	v_mfma_f32_16x16x32_bf16 v[94:97], v[154:157], v[178:181], v[94:97]
	v_mfma_f32_16x16x32_bf16 v[122:125], v[142:145], v[186:189], v[122:125]
	v_mfma_f32_16x16x32_bf16 v[90:93], v[154:157], v[186:189], v[90:93]
	v_mfma_f32_16x16x32_bf16 v[118:121], v[142:145], v[194:197], v[118:121]
	v_mfma_f32_16x16x32_bf16 v[86:89], v[154:157], v[194:197], v[86:89]
	v_mfma_f32_16x16x32_bf16 v[114:117], v[142:145], v[202:205], v[114:117]
	v_mfma_f32_16x16x32_bf16 v[82:85], v[154:157], v[202:205], v[82:85]
	s_setprio 0
	s_setprio 1
	v_mfma_f32_16x16x32_bf16 v[62:65], v[158:161], v[174:177], 0
	v_mfma_f32_16x16x32_bf16 v[30:33], v[166:169], v[174:177], 0
	v_mfma_f32_16x16x32_bf16 v[58:61], v[158:161], v[182:185], 0
	v_mfma_f32_16x16x32_bf16 v[26:29], v[166:169], v[182:185], 0
	v_mfma_f32_16x16x32_bf16 v[54:57], v[158:161], v[190:193], 0
	v_mfma_f32_16x16x32_bf16 v[22:25], v[166:169], v[190:193], 0
	v_mfma_f32_16x16x32_bf16 v[50:53], v[158:161], v[198:201], 0
	v_mfma_f32_16x16x32_bf16 v[18:21], v[166:169], v[198:201], 0
	v_mfma_f32_16x16x32_bf16 v[62:65], v[162:165], v[178:181], v[62:65]
	v_mfma_f32_16x16x32_bf16 v[30:33], v[170:173], v[178:181], v[30:33]
	v_mfma_f32_16x16x32_bf16 v[58:61], v[162:165], v[186:189], v[58:61]
	v_mfma_f32_16x16x32_bf16 v[26:29], v[170:173], v[186:189], v[26:29]
	v_mfma_f32_16x16x32_bf16 v[54:57], v[162:165], v[194:197], v[54:57]
	v_mfma_f32_16x16x32_bf16 v[22:25], v[170:173], v[194:197], v[22:25]
	v_mfma_f32_16x16x32_bf16 v[50:53], v[162:165], v[202:205], v[50:53]
	v_mfma_f32_16x16x32_bf16 v[18:21], v[170:173], v[202:205], v[18:21]
	s_setprio 0
	s_barrier
	s_add_i32 s74, s74, s22
	v_lshl_add_u64 v[214:215], s[62:63], 0, v[136:137]
	s_mov_b32 m0, s74
	ds_read_b128 v[174:177], v148 offset:16384
	ds_read_b128 v[178:181], v148 offset:17408
	ds_read_b128 v[182:185], v148 offset:18432
	ds_read_b128 v[186:189], v148 offset:19456
	ds_read_b128 v[190:193], v148 offset:20480
	ds_read_b128 v[194:197], v148 offset:21504
	ds_read_b128 v[198:201], v148 offset:22528
	ds_read_b128 v[202:205], v148 offset:23552
	global_load_lds_dwordx4 v[214:215], off
	s_add_i32 m0, s74, 0x2000
	v_lshl_add_u64 v[216:217], s[62:63], 0, v[134:135]
	s_add_u32 s62, s62, s4
	s_addc_u32 s63, s63, s5
	s_add_i32 s31, s31, s22
	global_load_lds_dwordx4 v[216:217], off
	v_lshl_add_u64 v[218:219], s[62:63], 0, v[136:137]
	s_mov_b32 m0, s31
	v_lshl_add_u64 v[220:221], s[62:63], 0, v[134:135]
	global_load_lds_dwordx4 v[218:219], off
	s_add_i32 m0, s31, 0x2000
	v_lshl_add_u64 v[222:223], s[20:21], 0, v[136:137]
	global_load_lds_dwordx4 v[220:221], off
	s_mov_b32 m0, s23
	v_lshl_add_u64 v[224:225], s[20:21], 0, v[134:135]
	global_load_lds_dwordx4 v[222:223], off
	s_mov_b32 m0, s52
	s_nop 0
	global_load_lds_dwordx4 v[224:225], off
	s_waitcnt vmcnt(8)
	s_waitcnt lgkmcnt(0)
	s_barrier
	s_setprio 1
	s_waitcnt lgkmcnt(0)
	v_mfma_f32_16x16x32_bf16 v[110:113], v[130:133], v[174:177], 0
	v_mfma_f32_16x16x32_bf16 v[78:81], v[150:153], v[174:177], 0
	v_mfma_f32_16x16x32_bf16 v[106:109], v[130:133], v[182:185], 0
	v_mfma_f32_16x16x32_bf16 v[74:77], v[150:153], v[182:185], 0
	v_mfma_f32_16x16x32_bf16 v[102:105], v[130:133], v[190:193], 0
	v_mfma_f32_16x16x32_bf16 v[70:73], v[150:153], v[190:193], 0
	v_mfma_f32_16x16x32_bf16 v[98:101], v[130:133], v[198:201], 0
	v_mfma_f32_16x16x32_bf16 v[66:69], v[150:153], v[198:201], 0
	v_mfma_f32_16x16x32_bf16 v[110:113], v[142:145], v[178:181], v[110:113]
	v_mfma_f32_16x16x32_bf16 v[78:81], v[154:157], v[178:181], v[78:81]
	v_mfma_f32_16x16x32_bf16 v[106:109], v[142:145], v[186:189], v[106:109]
	v_mfma_f32_16x16x32_bf16 v[74:77], v[154:157], v[186:189], v[74:77]
	v_mfma_f32_16x16x32_bf16 v[102:105], v[142:145], v[194:197], v[102:105]
	v_mfma_f32_16x16x32_bf16 v[70:73], v[154:157], v[194:197], v[70:73]
	v_mfma_f32_16x16x32_bf16 v[98:101], v[142:145], v[202:205], v[98:101]
	v_mfma_f32_16x16x32_bf16 v[66:69], v[154:157], v[202:205], v[66:69]
	s_setprio 0
	s_setprio 1
	v_mfma_f32_16x16x32_bf16 v[46:49], v[158:161], v[174:177], 0
	v_mfma_f32_16x16x32_bf16 v[14:17], v[166:169], v[174:177], 0
	v_mfma_f32_16x16x32_bf16 v[42:45], v[158:161], v[182:185], 0
	v_mfma_f32_16x16x32_bf16 v[10:13], v[166:169], v[182:185], 0
	v_mfma_f32_16x16x32_bf16 v[38:41], v[158:161], v[190:193], 0
	v_mfma_f32_16x16x32_bf16 v[6:9], v[166:169], v[190:193], 0
	v_mfma_f32_16x16x32_bf16 v[34:37], v[158:161], v[198:201], 0
	v_mfma_f32_16x16x32_bf16 v[2:5], v[166:169], v[198:201], 0
	v_mfma_f32_16x16x32_bf16 v[46:49], v[162:165], v[178:181], v[46:49]
	v_mfma_f32_16x16x32_bf16 v[14:17], v[170:173], v[178:181], v[14:17]
	v_mfma_f32_16x16x32_bf16 v[42:45], v[162:165], v[186:189], v[42:45]
	v_mfma_f32_16x16x32_bf16 v[10:13], v[170:173], v[186:189], v[10:13]
	v_mfma_f32_16x16x32_bf16 v[38:41], v[162:165], v[194:197], v[38:41]
	v_mfma_f32_16x16x32_bf16 v[6:9], v[170:173], v[194:197], v[6:9]
	v_mfma_f32_16x16x32_bf16 v[34:37], v[162:165], v[202:205], v[34:37]
	v_mfma_f32_16x16x32_bf16 v[2:5], v[170:173], v[202:205], v[2:5]
	s_setprio 0
	s_barrier
	s_add_i32 s31, 0, 0x18000
	v_add_u32_e32 v149, s31, v146
	s_add_i32 s62, 0, 0x1c000
	ds_read_b128 v[130:133], v149
	ds_read_b128 v[142:145], v149 offset:1024
	ds_read_b128 v[150:153], v149 offset:2048
	ds_read_b128 v[154:157], v149 offset:3072
	v_add_u32_e32 v149, s62, v146
	ds_read_b128 v[158:161], v149
	ds_read_b128 v[162:165], v149 offset:1024
	ds_read_b128 v[166:169], v149 offset:2048
	ds_read_b128 v[170:173], v149 offset:3072
	s_add_u32 s20, s20, s4
	s_addc_u32 s21, s21, s5
	s_mov_b32 m0, s53
	v_lshl_add_u64 v[226:227], s[20:21], 0, v[136:137]
	ds_read_b128 v[174:177], v148 offset:32768
	ds_read_b128 v[178:181], v148 offset:33792
	ds_read_b128 v[182:185], v148 offset:34816
	ds_read_b128 v[186:189], v148 offset:35840
	ds_read_b128 v[190:193], v148 offset:36864
	ds_read_b128 v[194:197], v148 offset:37888
	ds_read_b128 v[198:201], v148 offset:38912
	ds_read_b128 v[202:205], v148 offset:39936
	global_load_lds_dwordx4 v[226:227], off
	v_lshl_add_u64 v[226:227], s[20:21], 0, v[134:135]
	s_mov_b32 m0, s56
	s_nop 0
	global_load_lds_dwordx4 v[226:227], off
	s_waitcnt vmcnt(8)
	s_waitcnt lgkmcnt(0)
	s_barrier
	s_setprio 1
	s_waitcnt lgkmcnt(0)
	v_mfma_f32_16x16x32_bf16 v[126:129], v[130:133], v[174:177], v[126:129]
	v_mfma_f32_16x16x32_bf16 v[94:97], v[150:153], v[174:177], v[94:97]
	v_mfma_f32_16x16x32_bf16 v[122:125], v[130:133], v[182:185], v[122:125]
	v_mfma_f32_16x16x32_bf16 v[90:93], v[150:153], v[182:185], v[90:93]
	v_mfma_f32_16x16x32_bf16 v[118:121], v[130:133], v[190:193], v[118:121]
	v_mfma_f32_16x16x32_bf16 v[86:89], v[150:153], v[190:193], v[86:89]
	v_mfma_f32_16x16x32_bf16 v[114:117], v[130:133], v[198:201], v[114:117]
	v_mfma_f32_16x16x32_bf16 v[82:85], v[150:153], v[198:201], v[82:85]
	v_mfma_f32_16x16x32_bf16 v[126:129], v[142:145], v[178:181], v[126:129]
	v_mfma_f32_16x16x32_bf16 v[94:97], v[154:157], v[178:181], v[94:97]
	v_mfma_f32_16x16x32_bf16 v[122:125], v[142:145], v[186:189], v[122:125]
	v_mfma_f32_16x16x32_bf16 v[90:93], v[154:157], v[186:189], v[90:93]
	v_mfma_f32_16x16x32_bf16 v[118:121], v[142:145], v[194:197], v[118:121]
	v_mfma_f32_16x16x32_bf16 v[86:89], v[154:157], v[194:197], v[86:89]
	v_mfma_f32_16x16x32_bf16 v[114:117], v[142:145], v[202:205], v[114:117]
	v_mfma_f32_16x16x32_bf16 v[82:85], v[154:157], v[202:205], v[82:85]
	s_setprio 0
	s_setprio 1
	v_mfma_f32_16x16x32_bf16 v[62:65], v[158:161], v[174:177], v[62:65]
	v_mfma_f32_16x16x32_bf16 v[30:33], v[166:169], v[174:177], v[30:33]
	v_mfma_f32_16x16x32_bf16 v[58:61], v[158:161], v[182:185], v[58:61]
	v_mfma_f32_16x16x32_bf16 v[26:29], v[166:169], v[182:185], v[26:29]
	v_mfma_f32_16x16x32_bf16 v[54:57], v[158:161], v[190:193], v[54:57]
	v_mfma_f32_16x16x32_bf16 v[22:25], v[166:169], v[190:193], v[22:25]
	v_mfma_f32_16x16x32_bf16 v[50:53], v[158:161], v[198:201], v[50:53]
	v_mfma_f32_16x16x32_bf16 v[18:21], v[166:169], v[198:201], v[18:21]
	v_mfma_f32_16x16x32_bf16 v[62:65], v[162:165], v[178:181], v[62:65]
	v_mfma_f32_16x16x32_bf16 v[30:33], v[170:173], v[178:181], v[30:33]
	v_mfma_f32_16x16x32_bf16 v[58:61], v[162:165], v[186:189], v[58:61]
	v_mfma_f32_16x16x32_bf16 v[26:29], v[170:173], v[186:189], v[26:29]
	v_mfma_f32_16x16x32_bf16 v[54:57], v[162:165], v[194:197], v[54:57]
	v_mfma_f32_16x16x32_bf16 v[22:25], v[170:173], v[194:197], v[22:25]
	v_mfma_f32_16x16x32_bf16 v[50:53], v[162:165], v[202:205], v[50:53]
	v_mfma_f32_16x16x32_bf16 v[18:21], v[170:173], v[202:205], v[18:21]
	s_setprio 0
	s_barrier
	s_add_i32 s20, s31, s22
	v_lshl_add_u64 v[214:215], v[214:215], 0, s[60:61]
	s_mov_b32 m0, s20
	ds_read_b128 v[174:177], v148 offset:49152
	ds_read_b128 v[178:181], v148 offset:50176
	ds_read_b128 v[182:185], v148 offset:51200
	ds_read_b128 v[186:189], v148 offset:52224
	ds_read_b128 v[190:193], v148 offset:53248
	ds_read_b128 v[194:197], v148 offset:54272
	ds_read_b128 v[198:201], v148 offset:55296
	ds_read_b128 v[202:205], v148 offset:56320
	global_load_lds_dwordx4 v[214:215], off
	v_lshl_add_u64 v[214:215], v[216:217], 0, s[60:61]
	s_add_i32 m0, s20, 0x2000
	s_add_i32 s20, s62, s22
	global_load_lds_dwordx4 v[214:215], off
	v_lshl_add_u64 v[214:215], v[218:219], 0, s[60:61]
	s_mov_b32 m0, s20
	s_nop 0
	global_load_lds_dwordx4 v[214:215], off
	v_lshl_add_u64 v[214:215], v[220:221], 0, s[60:61]
	s_add_i32 m0, s20, 0x2000
	s_nop 0
	global_load_lds_dwordx4 v[214:215], off
	v_lshl_add_u64 v[214:215], v[222:223], 0, s[60:61]
	s_mov_b32 m0, s57
	s_nop 0
	global_load_lds_dwordx4 v[214:215], off
	v_lshl_add_u64 v[214:215], v[224:225], 0, s[60:61]
	s_mov_b32 m0, s65
	s_nop 0
	global_load_lds_dwordx4 v[214:215], off
	s_waitcnt vmcnt(8)
	s_waitcnt lgkmcnt(0)
	s_barrier
	s_setprio 1
	s_waitcnt lgkmcnt(0)
	v_mfma_f32_16x16x32_bf16 v[110:113], v[130:133], v[174:177], v[110:113]
	v_mfma_f32_16x16x32_bf16 v[78:81], v[150:153], v[174:177], v[78:81]
	v_mfma_f32_16x16x32_bf16 v[106:109], v[130:133], v[182:185], v[106:109]
	v_mfma_f32_16x16x32_bf16 v[74:77], v[150:153], v[182:185], v[74:77]
	v_mfma_f32_16x16x32_bf16 v[102:105], v[130:133], v[190:193], v[102:105]
	v_mfma_f32_16x16x32_bf16 v[70:73], v[150:153], v[190:193], v[70:73]
	v_mfma_f32_16x16x32_bf16 v[98:101], v[130:133], v[198:201], v[98:101]
	v_mfma_f32_16x16x32_bf16 v[66:69], v[150:153], v[198:201], v[66:69]
	v_mfma_f32_16x16x32_bf16 v[110:113], v[142:145], v[178:181], v[110:113]
	v_mfma_f32_16x16x32_bf16 v[78:81], v[154:157], v[178:181], v[78:81]
	v_mfma_f32_16x16x32_bf16 v[106:109], v[142:145], v[186:189], v[106:109]
	v_mfma_f32_16x16x32_bf16 v[74:77], v[154:157], v[186:189], v[74:77]
	v_mfma_f32_16x16x32_bf16 v[102:105], v[142:145], v[194:197], v[102:105]
	v_mfma_f32_16x16x32_bf16 v[70:73], v[154:157], v[194:197], v[70:73]
	v_mfma_f32_16x16x32_bf16 v[98:101], v[142:145], v[202:205], v[98:101]
	v_mfma_f32_16x16x32_bf16 v[66:69], v[154:157], v[202:205], v[66:69]
	s_setprio 0
	s_setprio 1
	v_mfma_f32_16x16x32_bf16 v[46:49], v[158:161], v[174:177], v[46:49]
	v_mfma_f32_16x16x32_bf16 v[14:17], v[166:169], v[174:177], v[14:17]
	v_mfma_f32_16x16x32_bf16 v[42:45], v[158:161], v[182:185], v[42:45]
	v_mfma_f32_16x16x32_bf16 v[10:13], v[166:169], v[182:185], v[10:13]
	v_mfma_f32_16x16x32_bf16 v[38:41], v[158:161], v[190:193], v[38:41]
	v_mfma_f32_16x16x32_bf16 v[6:9], v[166:169], v[190:193], v[6:9]
	v_mfma_f32_16x16x32_bf16 v[34:37], v[158:161], v[198:201], v[34:37]
	v_mfma_f32_16x16x32_bf16 v[2:5], v[166:169], v[198:201], v[2:5]
	v_mfma_f32_16x16x32_bf16 v[46:49], v[162:165], v[178:181], v[46:49]
	v_mfma_f32_16x16x32_bf16 v[14:17], v[170:173], v[178:181], v[14:17]
	v_mfma_f32_16x16x32_bf16 v[42:45], v[162:165], v[186:189], v[42:45]
	v_mfma_f32_16x16x32_bf16 v[10:13], v[170:173], v[186:189], v[10:13]
	v_mfma_f32_16x16x32_bf16 v[38:41], v[162:165], v[194:197], v[38:41]
	v_mfma_f32_16x16x32_bf16 v[6:9], v[170:173], v[194:197], v[6:9]
	v_mfma_f32_16x16x32_bf16 v[34:37], v[162:165], v[202:205], v[34:37]
	v_mfma_f32_16x16x32_bf16 v[2:5], v[170:173], v[202:205], v[2:5]
	s_setprio 0
	s_barrier
	s_add_u32 s18, s18, 0x100
	s_addc_u32 s19, s19, 0
	s_add_u32 s71, s71, 0x100
	s_addc_u32 s72, s72, 0
	s_cmp_ge_i32 s73, s66
	s_mov_b32 s20, s73
	s_cbranch_scc1 .LBB0_1013
